# scan exit: one of the two back-to-back workgroup barriers removed
# baseline (speedup 1.0000x reference)
; #define LAS __attribute__((address_space(3)))
; __device__ __forceinline__ void phase_attn(const Params& p, LAS unsigned char* lds) {
;     int tid_o = tid_of(p.wave_id);
;     const int tid = tid_o, lane = tid & 63, wave = __builtin_amdgcn_readfirstlane(tid >> 6);
;     const int qb = wave & 3, rw = wave >> 2, li = lane & 15, g = lane >> 4;
;     const bf16* QN = (const bf16*)(p.ws + WS_QN); const bf16* KN = (const bf16*)(p.ws + WS_KN); const bf16* VT = (const bf16*)(p.ws + WS_VN);
;     bf16* YB = (bf16*)p.out;
;     unsigned* ctr = (unsigned*)(p.ws + WS_ATTCTR);
;     LAS float* btab = (LAS float*)(lds + A_BIAS);
;     const float scale = 0.08838834764831845f * 1.4426950408889634f;
;     int krow_l[2], kch_l[2], vrow_l[2], vch_l[2];
; #pragma unroll
;     for (int e = 0; e < 2; ++e) { const int pk = 2 * wave + e; krow_l[e] = 4 * pk + (lane >> 4); kch_l[e] = (lane & 15) ^ (krow_l[e] & 15);
;         vrow_l[e] = 8 * pk + (lane >> 3); vch_l[e] = (lane & 7) ^ ((vrow_l[e] >> 1) & 7); }
;     const int myx = (int)(xb_xcc_id() & 7u);
;     int qoff = 0;
;     for (;;) {
;         if (tid == 0) { unsigned v = 0xffffffffu;
;             while (qoff < 8) { const int qx = (myx + qoff) & 7; const unsigned n = atomicAdd(ctr + 64 * qx, 1u); if (n < 64u) { v = (unsigned)((qx + 8 * (n >> 4)) * 16 + (n & 15)); break; } ++qoff; }
;             *(LAS unsigned*)(lds + A_ITEM) = v; }
;         __syncthreads();
;         const unsigned itu = *(LAS unsigned*)(lds + A_ITEM);
;         if (itu == 0xffffffffu) break;
;         const int it = (int)itu;
;         const int rp = it & 15, h = (it >> 4) & 7, b = it >> 7;
;         const int r = 2 * rp + rw;
;         const int rs = min(max(r - 4, 0), 24), ks0 = min(max(16 * qb - 8, 0), 32);
;         const int kr0 = min(max(2 * rp - 4, 0), 24), nband = min(max(2 * rp + 1 - 4, 0), 24) + 8 - kr0, NT = nband + 4;
;         const int cq = 16 * qb + li, cs = min(max(cq - 8, 0), 48);
;         const size_t qrow = (size_t)b * SEQ + r * GRID_W + cq;
;         float bvl = 0.f; if (tid < 15 * 31) bvl = p.rel_bias[h * 465 + tid];
;         bf16x8 qf[4];
; #pragma unroll
;         for (int ks = 0; ks < 4; ++ks) qf[ks] = *(const bf16x8*)(QN + qrow * WA + h * HD + 32 * ks + 8 * g);
; __global__ void __launch_bounds__(NTHREADS, 2) mega_fwd(Params p_in) {
;     ...
;         hgrn_scan(p, lds, bx); }
;       __syncthreads();
;       phase_attn(p, lds); }
.LBB0_435:
	s_mov_b32 s101, 1
.LBB0_436:
	s_waitcnt lgkmcnt(0)
	s_barrier
	s_waitcnt vmcnt(2)
	v_mbcnt_lo_u32_b32 v0, -1, 0
	v_mbcnt_hi_u32_b32 v0, -1, v0
	v_mov_b32_e32 v87, 0
	v_add_u32_e32 v85, s76, v0
	s_getreg_b32 s43, hwreg(HW_REG_XCC_ID, 0, 4)
	v_readfirstlane_b32 s34, v85
	s_ashr_i32 s3, s34, 6
	s_ashr_i32 s38, s34, 8
	s_add_u32 s39, s26, 0xdf42000
	s_addc_u32 s42, s27, 0
	s_lshl_b32 s4, s3, 1
	v_bfe_u32 v5, v85, 4, 2
	s_lshl_b32 s5, s3, 3
	s_or_b32 s4, s4, 1
	v_or_b32_e32 v0, s5, v5
	v_bitop3_b32 v3, s5, v85, v5 bitop3:0x36
	s_lshl_b32 s6, s3, 4
	s_lshl_b32 s5, s4, 2
	s_add_u32 s30, s26, 0xcf42000
	s_addc_u32 s31, s27, 0
	v_and_b32_e32 v10, 15, v85
	s_add_u32 s36, s26, 0xf142000
	v_bfe_u32 v1, v85, 3, 3
	s_addc_u32 s37, s27, 0
	v_lshlrev_b32_e32 v4, 3, v5
	s_waitcnt vmcnt(1)
	v_lshlrev_b32_e32 v15, 7, v10
	v_lshl_or_b32 v82, s4, 3, v1
	s_add_u32 s26, s26, 0x8000
	v_lshrrev_b32_e32 v13, 1, v85
	v_and_or_b32 v113, v4, 8, v15
	v_bfe_u32 v15, v85, 5, 1
	v_bitop3_b32 v19, v5, v10, 12 bitop3:0x36
	v_or_b32_e32 v80, s6, v1
	v_lshrrev_b32_e32 v1, 1, v82
	s_addc_u32 s27, s27, 0
	s_and_b32 s40, s6, 48
	v_bfe_u32 v6, v85, 1, 3
	v_lshlrev_b32_e32 v118, 4, v19
	v_bitop3_b32 v19, v13, v15, 7 bitop3:0x6c
	v_xor_b32_e32 v9, v1, v85
	v_sub_u32_e64 v1, s40, 8 clamp
	v_or_b32_e32 v84, s40, v10
	v_lshlrev_b32_e32 v119, 4, v19
	v_bitop3_b32 v19, v15, v6, 2 bitop3:0x36
	v_min_u32_e32 v11, 32, v1
	v_sub_u32_e64 v1, v84, 8 clamp
	v_lshlrev_b32_e32 v120, 4, v19
	v_bitop3_b32 v19, v15, v6, 4 bitop3:0x36
	v_bitop3_b32 v6, v15, v6, 6 bitop3:0x36
	v_min_u32_e32 v1, 48, v1
	v_lshlrev_b32_e32 v122, 4, v6
	v_lshlrev_b32_e32 v6, 2, v5
	v_lshlrev_b32_e32 v121, 4, v19
	v_add_u32_e32 v19, v11, v6
	v_add_u32_e32 v20, 16, v1
	v_cmp_ge_u32_e32 vcc, v19, v1
	v_cmp_lt_u32_e64 s[8:9], v19, v20
	v_or_b32_e32 v21, 1, v19
	s_and_b64 s[8:9], vcc, s[8:9]
	v_cmp_ge_u32_e32 vcc, v21, v1
	v_cmp_lt_u32_e64 s[10:11], v21, v20
	v_or_b32_e32 v21, 2, v19
	s_and_b64 s[10:11], vcc, s[10:11]
	v_cmp_ge_u32_e32 vcc, v21, v1
	v_cmp_lt_u32_e64 s[12:13], v21, v20
	v_or_b32_e32 v21, 3, v19
	s_and_b64 s[12:13], vcc, s[12:13]
	v_cmp_ge_u32_e32 vcc, v21, v1
	v_cmp_lt_u32_e64 s[14:15], v21, v20
	v_add_u32_e32 v21, 16, v19
	s_and_b64 s[14:15], vcc, s[14:15]
	v_cmp_ge_u32_e32 vcc, v21, v1
	v_cmp_lt_u32_e64 s[16:17], v19, v1
	v_add_u32_e32 v21, 17, v19
	s_and_b64 s[16:17], vcc, s[16:17]
	v_cmp_ge_u32_e32 vcc, v21, v1
	v_cmp_lt_u32_e64 s[18:19], v21, v20
	v_add_u32_e32 v21, 18, v19
	s_and_b64 s[18:19], vcc, s[18:19]
	v_cmp_ge_u32_e32 vcc, v21, v1
	v_cmp_lt_u32_e64 s[20:21], v21, v20
	v_add_u32_e32 v21, 19, v19
	s_and_b64 s[20:21], vcc, s[20:21]
	v_cmp_ge_u32_e32 vcc, v21, v1
	v_lshrrev_b32_e32 v1, 3, v11
	v_add_u32_e32 v1, v1, v15
	v_add_u32_e32 v15, 2, v1
	v_bitop3_b32 v1, v1, v13, 7 bitop3:0x78
	v_lshlrev_b32_e32 v123, 4, v1
	v_bitop3_b32 v1, v15, v13, 7 bitop3:0x78
	v_or_b32_e32 v2, s5, v5
	v_bitop3_b32 v8, s5, v85, v5 bitop3:0x36
	v_lshlrev_b32_e32 v124, 4, v1
	v_ashrrev_i32_e32 v1, 31, v0
	v_bitop3_b32 v7, v5, v85, 7 bitop3:0x78
	v_lshlrev_b64 v[88:89], 11, v[0:1]
	v_lshlrev_b32_e32 v0, 3, v3
	v_ashrrev_i32_e32 v3, 31, v2
	v_lshlrev_b32_e32 v1, 3, v8
	v_add_u32_e32 v12, v11, v10
	v_bitop3_b32 v16, v5, v85, 15 bitop3:0x78
	v_lshlrev_b64 v[90:91], 11, v[2:3]
	v_and_b32_e32 v2, 0x78, v1
	v_lshlrev_b32_e32 v86, 4, v7
	v_lshlrev_b32_e32 v1, 4, v9
	v_lshlrev_b32_e32 v14, 8, v12
	v_lshlrev_b32_e32 v115, 4, v16
	v_or_b32_e32 v16, 4, v5
	v_bitop3_b32 v17, v5, v10, 4 bitop3:0x36
	v_lshl_add_u64 v[92:93], s[36:37], 0, v[86:87]
	v_and_b32_e32 v86, 0x70, v1
	v_bitop3_b32 v1, v12, v5, 15 bitop3:0x6c
	v_lshlrev_b32_e32 v116, 4, v17
	v_or_b32_e32 v17, 8, v5
	v_bitop3_b32 v18, v5, v10, 8 bitop3:0x36
	v_lshl_or_b32 v125, v1, 4, v14
	v_bitop3_b32 v1, v12, v16, 15 bitop3:0x6c
	v_lshlrev_b32_e32 v117, 4, v18
	v_or_b32_e32 v18, 12, v5
	v_lshl_or_b32 v126, v1, 4, v14
	v_bitop3_b32 v1, v12, v17, 15 bitop3:0x6c
	v_lshl_or_b32 v127, v1, 4, v14
	v_bitop3_b32 v1, v12, v18, 15 bitop3:0x6c
	v_lshl_or_b32 v128, v1, 4, v14
	v_sub_u32_e32 v1, v19, v10
	v_subrev_u32_e32 v1, s40, v1
	v_lshlrev_b32_e32 v129, 2, v1
	v_and_b32_e32 v1, 48, v85
	v_lshl_add_u32 v1, v11, 2, v1
	v_lshlrev_b32_e32 v3, 2, v10
	s_lshl_b32 s3, s3, 11
	v_sub_u32_e32 v1, v1, v3
	s_and_b32 s34, s34, 0xc0
	s_movk_i32 s6, 0x1d1
	s_add_i32 s44, s3, 0
	s_add_i32 s3, 0, 0x20000
	v_cmp_lt_u32_e64 s[22:23], v21, v20
	v_and_b32_e32 v0, 0x78, v0
	v_subrev_u32_e32 v1, s34, v1
	s_mul_i32 s34, s38, 0x7c
	s_mov_b32 s35, 0
	v_cmp_eq_u32_e64 s[4:5], 0, v85
	v_cmp_gt_i32_e64 s[6:7], s6, v85
	s_add_i32 s45, s44, 0x8000
	v_lshl_add_u32 v112, v85, 2, s3
	v_lshlrev_b32_e32 v114, 8, v10
	s_and_b64 s[22:23], vcc, s[22:23]
	v_ashrrev_i32_e32 v81, 31, v80
	v_ashrrev_i32_e32 v83, 31, v82
	v_lshl_add_u64 v[94:95], s[36:37], 0, v[86:87]
	s_sub_i32 s37, 0, s38
	v_subrev_u32_e32 v130, s34, v1
	v_mov_b32_e32 v131, 1
	s_add_i32 s47, 0, 0x20800
	v_lshlrev_b32_e32 v86, 1, v4
	v_lshlrev_b32_e32 v96, 1, v0
	v_lshlrev_b32_e32 v98, 1, v2
	s_movk_i32 s49, 0x1200
	s_mov_b32 s36, 0x3e0293ee
	s_mov_b32 s62, 0xf149f2ca
	v_lshlrev_b32_e32 v100, 1, v6
	v_mov_b32_e32 v132, 0xf149f2ca
	v_mov_b32_e32 v133, v87
	s_branch .LBB0_438
